# attention unit prologue: both bound-table load pairs issued together (counted waits)
# baseline (speedup 1.0000x reference)
; __device__ __forceinline__ void attn_unit(const Params& p, LAS unsigned char* lds, int bh, int qb) {
;     ...
;     for (int ks = 0; ks < 6; ++ks) qr[ks] = *(const bf16x8*)(Qg + 16 * ks + 8 * hi);
;     bool fast;
;     { float gq = fabsf(p.in[8][lane]), gk = fabsf(p.in[9][lane]);
;       if (lane < 32) { gq = fmaxf(gq, fabsf(p.in[8][64 + lane])); gk = fmaxf(gk, fabsf(p.in[9][64 + lane])); }
; #pragma unroll
;       for (int o = 1; o < 64; o <<= 1) { gq = fmaxf(gq, __shfl_xor(gq, o)); gk = fmaxf(gk, __shfl_xor(gk, o)); }
;       fast = __builtin_amdgcn_readfirstlane((14.2f * gq * gk < 40.0f) ? 1 : 0) != 0; }
.LBB0_715:
	s_ashr_i32 s38, s92, 3
	v_mov_b32_e32 v166, v163
	s_ashr_i32 s39, s38, 31
	s_lshl_b32 s2, s92, 8
	s_lshl_b64 s[0:1], s[38:39], 11
	v_ashrrev_i32_e32 v167, 6, v166
	s_and_b32 s16, s2, 0x700
	v_and_b32_e32 v164, 31, v166
	s_or_b32 s0, s0, s16
	v_lshlrev_b32_e32 v136, 5, v167
	v_ashrrev_i32_e32 v137, 31, v136
	v_or_b32_e32 v2, s0, v164
	v_mov_b32_e32 v3, s1
	v_lshl_add_u64 v[2:3], v[2:3], 0, v[136:137]
	v_bfe_u32 v168, v166, 5, 1
	s_waitcnt lgkmcnt(0)
	v_mad_u64_u32 v[4:5], s[0:1], v2, s96, v[134:135]
	v_mad_i32_i24 v5, v3, s96, v5
	v_lshlrev_b32_e32 v132, 4, v168
	s_waitcnt lgkmcnt(0)
	v_lshl_add_u64 v[6:7], v[4:5], 0, v[132:133]
	global_load_dwordx4 v[112:115], v[6:7], off
	global_load_dwordx4 v[108:111], v[6:7], off offset:32
	global_load_dwordx4 v[104:107], v[6:7], off offset:64
	global_load_dwordx4 v[100:103], v[6:7], off offset:96
	v_and_b32_e32 v165, 63, v166
	v_readlane_b32 s0, v244, 3
	v_lshlrev_b32_e32 v2, 2, v165
	v_readlane_b32 s1, v244, 4
	v_readlane_b32 s2, v244, 5
	v_readlane_b32 s3, v244, 6
	s_nop 2
	global_load_dword v1, v2, s[0:1]
	s_nop 0
	global_load_dword v4, v2, s[2:3]
	v_cmp_gt_u32_e32 vcc, 32, v165
	s_and_saveexec_b64 s[40:41], vcc
	global_load_dword v8, v2, s[0:1] offset:256
	global_load_dword v9, v2, s[2:3] offset:256
	s_or_b64 exec, exec, s[40:41]
	global_load_dwordx4 v[116:119], v[6:7], off offset:128
	global_load_dwordx4 v[96:99], v[6:7], off offset:160
	v_cmp_gt_u32_e64 s[2:3], 32, v165
	v_readlane_b32 s4, v244, 7
	v_readlane_b32 s5, v244, 8
	v_readlane_b32 s6, v244, 9
	v_readlane_b32 s7, v244, 10
	v_readlane_b32 s8, v244, 11
	v_readlane_b32 s9, v244, 12
	v_readlane_b32 s10, v244, 13
	v_readlane_b32 s11, v244, 14
	v_readlane_b32 s12, v244, 15
	v_readlane_b32 s13, v244, 16
	v_readlane_b32 s14, v244, 17
	v_readlane_b32 s15, v244, 18
	s_waitcnt vmcnt(5)
	v_and_b32_e32 v5, 0x7fffffff, v1
	s_waitcnt vmcnt(4)
	v_and_b32_e32 v3, 0x7fffffff, v4
	s_and_saveexec_b64 s[0:1], s[2:3]
	s_cbranch_execz .LBB0_717
	v_readlane_b32 s40, v244, 3
	v_mov_b32_e32 v3, v133
	v_readlane_b32 s41, v244, 4
	v_readlane_b32 s42, v244, 5
	v_readlane_b32 s43, v244, 6
	v_lshl_add_u64 v[6:7], s[40:41], 0, v[2:3]
	v_max_f32_e64 v1, |v1|, |v1|
	v_lshl_add_u64 v[2:3], s[42:43], 0, v[2:3]
	v_max_f32_e64 v3, |v4|, |v4|
	v_readlane_b32 s44, v244, 7
	v_readlane_b32 s45, v244, 8
	v_readlane_b32 s46, v244, 9
	v_readlane_b32 s47, v244, 10
	v_readlane_b32 s48, v244, 11
	v_readlane_b32 s49, v244, 12
	v_readlane_b32 s50, v244, 13
	v_readlane_b32 s51, v244, 14
	v_readlane_b32 s52, v244, 15
	v_readlane_b32 s53, v244, 16
	v_readlane_b32 s54, v244, 17
	v_readlane_b32 s55, v244, 18
	s_waitcnt vmcnt(3)
	v_max_f32_e64 v4, |v8|, |v8|
	s_waitcnt vmcnt(2)
	v_max_f32_e64 v2, |v9|, |v9|
	v_max_f32_e32 v5, v1, v4
	v_max_f32_e32 v3, v3, v2
